# final RMSNorm rows XCD-aligned (8 consecutive rows per wave inside the owning XCD's range) so the 16->17 seam is an XCD-local barrier (no L2 write-back / top level) and XB is read from the local L2
# speedup vs baseline: 1.0060x; 1.0060x over previous
.LBB0_26:
	s_cmp_gt_i32 s74, 9
	v_mov_b32_e32 v245, v224
	s_mov_b32 s80, s94
	s_mov_b32 s73, s74
	s_cselect_b64 s[6:7], -1, 0
	s_mov_b64 s[0:1], -1
	s_mov_b64 s[52:53], 0
	s_cmp_lt_i32 s74, 9
	s_mov_b64 s[12:13], 0
	s_mov_b64 s[88:89], 0
	s_mov_b64 s[94:95], 0
	s_mov_b64 s[96:97], 0
	s_mov_b64 s[28:29], 0
	s_mov_b64 s[98:99], 0
	s_cbranch_scc1 .LBB0_98
	s_mov_b64 s[54:55], -1
	s_mov_b64 s[56:57], 0
	s_cmp_gt_i32 s73, 12
	s_cbranch_scc0 .LBB0_42
	s_cmp_gt_i32 s73, 14
	s_cbranch_scc0 .LBB0_39
	s_mov_b64 s[28:29], -1
	s_mov_b64 s[0:1], 0
	s_cmp_gt_i32 s73, 15
	s_cbranch_scc0 .LBB0_39
	s_mov_b64 s[98:99], -1
	s_mov_b64 s[28:29], 0
	s_cmp_gt_i32 s73, 16
	s_cbranch_scc0 .LBB0_39
	s_cmp_eq_u32 s73, 17
	s_mov_b64 s[12:13], -1
	s_cbranch_scc0 .LBB0_38
	s_waitcnt lgkmcnt(0)
	v_ashrrev_i32_e32 v2, 6, v245
	v_lshlrev_b32_e32 v2, 3, v2
	v_readlane_b32 s4, v253, 49
	s_movk_i32 s2, 0x4000
	v_readlane_b32 s5, v253, 50
	v_mov_b32_e32 v8, 0
	v_cmp_gt_i32_e32 vcc, s2, v8
	s_and_saveexec_b64 s[30:31], vcc
	s_mov_b32 s40, 64
	s_mov_b32 s41, 0
	s_cbranch_execz .LBB0_37
	v_cmp_lt_i32_e64 s[36:37], v229, v228
	v_ashrrev_i32_e32 v3, 31, v2
	v_and_b32_e32 v15, 63, v245
	v_cndmask_b32_e64 v0, v227, v229, s[36:37]
	v_cmp_lt_i32_e64 s[36:37], v230, v228
	v_lshlrev_b32_e32 v9, 2, v0
	v_lshlrev_b32_e32 v4, 2, v15
	v_cndmask_b32_e64 v0, v227, v230, s[36:37]
	v_cmp_lt_i32_e64 s[36:37], v231, v228
	v_lshlrev_b32_e32 v10, 2, v0
	v_mov_b32_e32 v5, v97
	v_cndmask_b32_e64 v0, v227, v231, s[36:37]
	v_cmp_lt_i32_e64 s[36:37], v232, v228
	v_lshlrev_b32_e32 v11, 2, v0
	v_lshlrev_b32_e32 v96, 5, v15
	v_cndmask_b32_e64 v0, v227, v232, s[36:37]
	v_cmp_lt_i32_e64 s[36:37], v233, v228
	v_lshlrev_b32_e32 v12, 2, v0
	v_cmp_gt_u32_e32 vcc, 16, v15
	v_cndmask_b32_e64 v0, v227, v233, s[36:37]
	v_cmp_lt_i32_e64 s[36:37], v234, v228
	v_lshlrev_b32_e32 v13, 2, v0
	s_mov_b64 s[38:39], 0
	v_cndmask_b32_e64 v0, v227, v234, s[36:37]
	s_mov_b64 s[36:37], s[6:7]
	v_readlane_b32 s4, v253, 58
	v_readlane_b32 s5, v253, 59
	v_readlane_b32 s4, v253, 49
	v_readlane_b32 s5, v253, 50
	s_nop 3
	s_lshr_b32 s101, s4, 8
	s_lshl_b32 s101, s101, 11
	s_and_b32 s4, s4, 0xff
	s_lshl_b32 s4, s4, 3
	s_or_b32 s4, s4, s101
	v_readlane_b32 s6, v253, 60
	v_readlane_b32 s7, v253, 61
	v_lshl_add_u64 v[6:7], s[4:5], 0, v[2:3]
	v_lshlrev_b64 v[2:3], 6, v[6:7]
	v_lshl_add_u64 v[2:3], v[2:3], 0, v[4:5]
	v_readlane_b32 s4, v252, 26
	v_lshlrev_b64 v[4:5], 11, v[6:7]
	v_lshlrev_b64 v[6:7], 12, v[6:7]
	v_readlane_b32 s18, v251, 8
	v_readlane_b32 s19, v251, 9
	v_readlane_b32 s5, v252, 27
	v_lshl_or_b32 v4, v15, 4, v4
	v_or_b32_e32 v6, v6, v96
	v_lshlrev_b32_e32 v14, 2, v0
	v_lshl_add_u64 v[0:1], s[18:19], 0, v[96:97]
	s_mov_b64 s[6:7], s[36:37]
	v_lshl_add_u64 v[2:3], s[4:5], 0, v[2:3]
	v_lshl_add_u64 v[4:5], s[22:23], 0, v[4:5]
	v_lshl_add_u64 v[6:7], s[84:85], 0, v[6:7]
	v_readlane_b32 s8, v253, 62
	v_readlane_b32 s9, v253, 63
	v_readlane_b32 s10, v251, 0
	v_readlane_b32 s11, v251, 1
	v_readlane_b32 s12, v251, 2
	v_readlane_b32 s13, v251, 3
	v_readlane_b32 s14, v251, 4
	v_readlane_b32 s15, v251, 5
	v_readlane_b32 s16, v251, 6
	v_readlane_b32 s17, v251, 7
	s_branch .LBB0_35
.LBB0_34:
	s_or_b64 exec, exec, s[36:37]
	global_load_dwordx4 v[16:19], v[4:5], off nt
	global_load_dwordx4 v[20:23], v[0:1], off
	global_load_dwordx4 v[24:27], v[0:1], off offset:16
	s_waitcnt vmcnt(0)
	ds_bpermute_b32 v28, v9, v15
	s_mov_b32 s4, 0x800
	s_mov_b32 s5, 0
	v_add_u32_e32 v8, 1, v8
	s_movk_i32 s2, 7
	s_waitcnt lgkmcnt(0)
	v_add_f32_e32 v15, v15, v28
	ds_bpermute_b32 v28, v10, v15
	v_lshl_add_u64 v[2:3], v[2:3], 0, s[40:41]
	s_waitcnt lgkmcnt(0)
	v_add_f32_e32 v15, v15, v28
	ds_bpermute_b32 v28, v11, v15
	s_waitcnt lgkmcnt(0)
	v_add_f32_e32 v15, v15, v28
	ds_bpermute_b32 v28, v12, v15
	s_waitcnt lgkmcnt(0)
	v_add_f32_e32 v15, v15, v28
	ds_bpermute_b32 v28, v13, v15
	s_waitcnt lgkmcnt(0)
	v_add_f32_e32 v15, v15, v28
	ds_bpermute_b32 v28, v14, v15
	s_waitcnt lgkmcnt(0)
	v_add_f32_e32 v15, v15, v28
	v_fmamk_f32 v15, v15, 0x3a800000, v225
	v_mul_f32_e32 v28, 0x4b800000, v15
	v_cmp_gt_f32_e64 s[36:37], s3, v15
	s_waitcnt vmcnt(2)
	v_lshlrev_b32_e32 v30, 16, v16
	v_cndmask_b32_e64 v15, v15, v28, s[36:37]
	v_rsq_f32_e32 v15, v15
	v_and_b32_e32 v31, 0xffff0000, v16
	v_lshlrev_b32_e32 v16, 16, v17
	v_and_b32_e32 v17, 0xffff0000, v17
	v_mul_f32_e32 v28, 0x45800000, v15
	v_cndmask_b32_e64 v28, v15, v28, s[36:37]
	v_lshlrev_b32_e32 v32, 16, v18
	v_and_b32_e32 v33, 0xffff0000, v18
	v_lshlrev_b32_e32 v18, 16, v19
	v_and_b32_e32 v19, 0xffff0000, v19
	v_pk_mul_f32 v[30:31], v[28:29], v[30:31] op_sel_hi:[0,1]
	v_pk_mul_f32 v[16:17], v[28:29], v[16:17] op_sel_hi:[0,1]
	v_pk_mul_f32 v[32:33], v[28:29], v[32:33] op_sel_hi:[0,1]
	v_pk_mul_f32 v[34:35], v[28:29], v[18:19] op_sel_hi:[0,1]
	s_waitcnt vmcnt(1)
	v_pk_mul_f32 v[18:19], v[22:23], v[16:17]
	v_pk_mul_f32 v[16:17], v[20:21], v[30:31]
	s_waitcnt vmcnt(0)
	v_pk_mul_f32 v[22:23], v[26:27], v[34:35]
	v_pk_mul_f32 v[20:21], v[24:25], v[32:33]
	global_store_dwordx4 v[6:7], v[16:19], off nt
	global_store_dwordx4 v[6:7], v[20:23], off offset:16 nt
	global_load_dwordx4 v[16:19], v[4:5], off offset:1024 nt
	s_nop 0
	global_load_dwordx4 v[20:23], v[0:1], off offset:2048
	global_load_dwordx4 v[24:27], v[0:1], off offset:2064
	v_lshl_add_u64 v[4:5], v[4:5], 0, s[4:5]
	s_mov_b32 s4, 0x1000
	v_cmp_lt_i32_e64 s[36:37], s2, v8
	s_mov_b32 s5, 0
	s_or_b64 s[38:39], s[36:37], s[38:39]
	s_waitcnt vmcnt(2)
	v_lshlrev_b32_e32 v30, 16, v16
	v_and_b32_e32 v31, 0xffff0000, v16
	v_lshlrev_b32_e32 v16, 16, v17
	v_and_b32_e32 v17, 0xffff0000, v17
	v_lshlrev_b32_e32 v32, 16, v18
	v_and_b32_e32 v33, 0xffff0000, v18
	v_lshlrev_b32_e32 v18, 16, v19
	v_and_b32_e32 v19, 0xffff0000, v19
	v_pk_mul_f32 v[30:31], v[28:29], v[30:31] op_sel_hi:[0,1]
	v_pk_mul_f32 v[16:17], v[28:29], v[16:17] op_sel_hi:[0,1]
	v_pk_mul_f32 v[32:33], v[28:29], v[32:33] op_sel_hi:[0,1]
	v_pk_mul_f32 v[28:29], v[28:29], v[18:19] op_sel_hi:[0,1]
	s_waitcnt vmcnt(1)
	v_pk_mul_f32 v[18:19], v[22:23], v[16:17]
	v_pk_mul_f32 v[16:17], v[20:21], v[30:31]
	s_waitcnt vmcnt(0)
	v_pk_mul_f32 v[22:23], v[26:27], v[28:29]
	v_pk_mul_f32 v[20:21], v[24:25], v[32:33]
	global_store_dwordx4 v[6:7], v[16:19], off offset:2048 nt
	global_store_dwordx4 v[6:7], v[20:23], off offset:2064 nt
	v_lshl_add_u64 v[6:7], v[6:7], 0, s[4:5]
	s_andn2_b64 exec, exec, s[38:39]
	s_cbranch_execz .LBB0_37

.LBB0_611:
	s_andn2_saveexec_b64 s[4:5], s[30:31]
	s_cbranch_execz .LBB0_24
	s_mov_b64 s[30:31], exec
	s_cmp_eq_u32 s100, 0
	s_cbranch_scc1 .Lglobal_bar
	s_cmp_eq_u32 s73, 3
	s_cbranch_scc1 .Llocal_bar
	s_cmp_eq_u32 s73, 5
	s_cbranch_scc1 .Llocal_bar
	s_cmp_eq_u32 s73, 7
	s_cbranch_scc1 .Llocal_bar
	s_cmp_eq_u32 s73, 11
	s_cbranch_scc1 .Llocal_bar
	s_cmp_eq_u32 s73, 13
	s_cbranch_scc1 .Llocal_bar
	s_cmp_eq_u32 s73, 15
	s_cbranch_scc1 .Llocal_bar
	s_cmp_eq_u32 s73, 16
	s_cbranch_scc1 .Llocal_bar
	s_branch .Lglobal_bar
